# adds to the previous version: phase B epilogue second-half row scale via op_sel_hi broadcast instead of 3 v_mov + s_nop per row group
# baseline (speedup 1.0000x reference)
; __device__ __forceinline__ unsigned cvt_pk_bf16(float lo, float hi) { f32x2 v = {lo, hi}; bf16x2_t b = __builtin_convertvector(v, bf16x2_t); return __builtin_bit_cast(unsigned, b); }
;     __device__ __forceinline__ void operator()(const f32x4 (&acc)[2][2][4][2], const Unit& u, int wr, int wc, int fr, int fq) const {
;     ...
;                 for (int bj = 0; bj < 2; ++bj) { const f32x4 v0 = acc[ai][bj][m][0] * s, v1 = acc[ai][bj][m][1] * s; u32x4 w;
;                     w.x = cvt_pk_bf16(v0[0], v0[1]); w.y = cvt_pk_bf16(v0[2], v0[3]); w.z = cvt_pk_bf16(v1[0], v1[1]); w.w = cvt_pk_bf16(v1[2], v1[3]);
;                     if (kvt) { const int c = col0 + bj * HALF; int hd, off;
;                         if (colt < 2048) { const int cp = c - 1024, d = cp & 63; hd = (cp >> 6) & 7; off = (cp >> 9) * 8192 + kv * 128 + (((d >> 3) ^ ((kv >> 1) & 7)) << 4); }
;                         else { const int cp = c - 2048, d = cp & 127; hd = cp >> 7; off = 16384 + (d >> 5) * 4096 + kv * 64 + (((d >> 3) & 3) << 4); }
;                         *(u32x4*)(KV + ((size_t)((((seq << 3) + hd) << (sshift - 6)) + tile) << 15) + off) = w; }
;                     else *(u32x4*)(rowp + bj * HALF) = w; } }
.LBB0_98:
	v_pk_mul_f32 v[118:119], v[118:119], v[138:139] op_sel_hi:[1,0]
	v_pk_mul_f32 v[120:121], v[120:121], v[138:139] op_sel_hi:[1,0]
	v_pk_mul_f32 v[122:123], v[116:117], v[138:139] op_sel_hi:[1,0]
	v_pk_mul_f32 v[116:117], v[114:115], v[138:139] op_sel_hi:[1,0]
	v_cvt_pk_bf16_f32 v114, v118, v119
	v_cndmask_b32_e64 v118, 0, 1, s[26:27]
	v_cvt_pk_bf16_f32 v115, v120, v121
	v_cvt_pk_bf16_f32 v116, v116, v117
	v_cvt_pk_bf16_f32 v117, v122, v123
	v_cmp_ne_u32_e64 s[8:9], 1, v118
	s_andn2_b64 vcc, exec, s[26:27]
	s_mov_b64 s[26:27], -1
	s_cbranch_vccnz .LBB0_100
	s_mov_b64 s[26:27], 0
	global_store_dwordx4 v[136:137], v[114:117], off offset:256

; __device__ __forceinline__ unsigned cvt_pk_bf16(float lo, float hi) { f32x2 v = {lo, hi}; bf16x2_t b = __builtin_convertvector(v, bf16x2_t); return __builtin_bit_cast(unsigned, b); }
;     __device__ __forceinline__ void operator()(const f32x4 (&acc)[2][2][4][2], const Unit& u, int wr, int wc, int fr, int fq) const {
;     ...
;                 for (int bj = 0; bj < 2; ++bj) { const f32x4 v0 = acc[ai][bj][m][0] * s, v1 = acc[ai][bj][m][1] * s; u32x4 w;
;                     w.x = cvt_pk_bf16(v0[0], v0[1]); w.y = cvt_pk_bf16(v0[2], v0[3]); w.z = cvt_pk_bf16(v1[0], v1[1]); w.w = cvt_pk_bf16(v1[2], v1[3]);
;                     if (kvt) { const int c = col0 + bj * HALF; int hd, off;
;                         if (colt < 2048) { const int cp = c - 1024, d = cp & 63; hd = (cp >> 6) & 7; off = (cp >> 9) * 8192 + kv * 128 + (((d >> 3) ^ ((kv >> 1) & 7)) << 4); }
;                         else { const int cp = c - 2048, d = cp & 127; hd = cp >> 7; off = 16384 + (d >> 5) * 4096 + kv * 64 + (((d >> 3) & 3) << 4); }
;                         *(u32x4*)(KV + ((size_t)((((seq << 3) + hd) << (sshift - 6)) + tile) << 15) + off) = w; }
;                     else *(u32x4*)(rowp + bj * HALF) = w; } }
.LBB0_106:
	v_pk_mul_f32 v[104:105], v[104:105], v[116:117] op_sel_hi:[1,0]
	v_pk_mul_f32 v[102:103], v[102:103], v[116:117] op_sel_hi:[1,0]
	v_pk_mul_f32 v[106:107], v[100:101], v[116:117] op_sel_hi:[1,0]
	v_pk_mul_f32 v[100:101], v[98:99], v[116:117] op_sel_hi:[1,0]
	v_cvt_pk_bf16_f32 v98, v102, v103
	v_cvt_pk_bf16_f32 v99, v104, v105
	v_cvt_pk_bf16_f32 v100, v100, v101
	v_cvt_pk_bf16_f32 v101, v106, v107
	s_and_b64 vcc, exec, s[8:9]
	s_mov_b64 s[26:27], -1
	s_cbranch_vccnz .LBB0_108
	s_mov_b64 s[26:27], 0
	global_store_dwordx4 v[114:115], v[98:101], off offset:256

; __device__ __forceinline__ unsigned cvt_pk_bf16(float lo, float hi) { f32x2 v = {lo, hi}; bf16x2_t b = __builtin_convertvector(v, bf16x2_t); return __builtin_bit_cast(unsigned, b); }
;     __device__ __forceinline__ void operator()(const f32x4 (&acc)[2][2][4][2], const Unit& u, int wr, int wc, int fr, int fq) const {
;     ...
;                 for (int bj = 0; bj < 2; ++bj) { const f32x4 v0 = acc[ai][bj][m][0] * s, v1 = acc[ai][bj][m][1] * s; u32x4 w;
;                     w.x = cvt_pk_bf16(v0[0], v0[1]); w.y = cvt_pk_bf16(v0[2], v0[3]); w.z = cvt_pk_bf16(v1[0], v1[1]); w.w = cvt_pk_bf16(v1[2], v1[3]);
;                     if (kvt) { const int c = col0 + bj * HALF; int hd, off;
;                         if (colt < 2048) { const int cp = c - 1024, d = cp & 63; hd = (cp >> 6) & 7; off = (cp >> 9) * 8192 + kv * 128 + (((d >> 3) ^ ((kv >> 1) & 7)) << 4); }
;                         else { const int cp = c - 2048, d = cp & 127; hd = cp >> 7; off = 16384 + (d >> 5) * 4096 + kv * 64 + (((d >> 3) & 3) << 4); }
;                         *(u32x4*)(KV + ((size_t)((((seq << 3) + hd) << (sshift - 6)) + tile) << 15) + off) = w; }
;                     else *(u32x4*)(rowp + bj * HALF) = w; } }
.LBB0_114:
	v_pk_mul_f32 v[88:89], v[88:89], v[100:101] op_sel_hi:[1,0]
	v_pk_mul_f32 v[86:87], v[86:87], v[100:101] op_sel_hi:[1,0]
	v_pk_mul_f32 v[90:91], v[84:85], v[100:101] op_sel_hi:[1,0]
	v_pk_mul_f32 v[84:85], v[82:83], v[100:101] op_sel_hi:[1,0]
	v_cvt_pk_bf16_f32 v82, v86, v87
	v_cvt_pk_bf16_f32 v83, v88, v89
	v_cvt_pk_bf16_f32 v84, v84, v85
	v_cvt_pk_bf16_f32 v85, v90, v91
	s_and_b64 vcc, exec, s[8:9]
	s_mov_b64 s[26:27], -1
	s_cbranch_vccnz .LBB0_116
	s_mov_b64 s[26:27], 0
	global_store_dwordx4 v[98:99], v[82:85], off offset:256

; __device__ __forceinline__ unsigned cvt_pk_bf16(float lo, float hi) { f32x2 v = {lo, hi}; bf16x2_t b = __builtin_convertvector(v, bf16x2_t); return __builtin_bit_cast(unsigned, b); }
;     __device__ __forceinline__ void operator()(const f32x4 (&acc)[2][2][4][2], const Unit& u, int wr, int wc, int fr, int fq) const {
;     ...
;                 for (int bj = 0; bj < 2; ++bj) { const f32x4 v0 = acc[ai][bj][m][0] * s, v1 = acc[ai][bj][m][1] * s; u32x4 w;
;                     w.x = cvt_pk_bf16(v0[0], v0[1]); w.y = cvt_pk_bf16(v0[2], v0[3]); w.z = cvt_pk_bf16(v1[0], v1[1]); w.w = cvt_pk_bf16(v1[2], v1[3]);
;                     if (kvt) { const int c = col0 + bj * HALF; int hd, off;
;                         if (colt < 2048) { const int cp = c - 1024, d = cp & 63; hd = (cp >> 6) & 7; off = (cp >> 9) * 8192 + kv * 128 + (((d >> 3) ^ ((kv >> 1) & 7)) << 4); }
;                         else { const int cp = c - 2048, d = cp & 127; hd = cp >> 7; off = 16384 + (d >> 5) * 4096 + kv * 64 + (((d >> 3) & 3) << 4); }
;                         *(u32x4*)(KV + ((size_t)((((seq << 3) + hd) << (sshift - 6)) + tile) << 15) + off) = w; }
;                     else *(u32x4*)(rowp + bj * HALF) = w; } }
.LBB0_122:
	v_pk_mul_f32 v[72:73], v[72:73], v[84:85] op_sel_hi:[1,0]
	v_pk_mul_f32 v[70:71], v[70:71], v[84:85] op_sel_hi:[1,0]
	v_pk_mul_f32 v[74:75], v[68:69], v[84:85] op_sel_hi:[1,0]
	v_pk_mul_f32 v[68:69], v[66:67], v[84:85] op_sel_hi:[1,0]
	v_cvt_pk_bf16_f32 v66, v70, v71
	v_cvt_pk_bf16_f32 v67, v72, v73
	v_cvt_pk_bf16_f32 v68, v68, v69
	v_cvt_pk_bf16_f32 v69, v74, v75
	s_and_b64 vcc, exec, s[8:9]
	s_mov_b64 s[26:27], -1
	s_cbranch_vccnz .LBB0_124
	s_mov_b64 s[26:27], 0
	global_store_dwordx4 v[82:83], v[66:69], off offset:256

; __device__ __forceinline__ unsigned cvt_pk_bf16(float lo, float hi) { f32x2 v = {lo, hi}; bf16x2_t b = __builtin_convertvector(v, bf16x2_t); return __builtin_bit_cast(unsigned, b); }
;     __device__ __forceinline__ void operator()(const f32x4 (&acc)[2][2][4][2], const Unit& u, int wr, int wc, int fr, int fq) const {
;     ...
;                 for (int bj = 0; bj < 2; ++bj) { const f32x4 v0 = acc[ai][bj][m][0] * s, v1 = acc[ai][bj][m][1] * s; u32x4 w;
;                     w.x = cvt_pk_bf16(v0[0], v0[1]); w.y = cvt_pk_bf16(v0[2], v0[3]); w.z = cvt_pk_bf16(v1[0], v1[1]); w.w = cvt_pk_bf16(v1[2], v1[3]);
;                     if (kvt) { const int c = col0 + bj * HALF; int hd, off;
;                         if (colt < 2048) { const int cp = c - 1024, d = cp & 63; hd = (cp >> 6) & 7; off = (cp >> 9) * 8192 + kv * 128 + (((d >> 3) ^ ((kv >> 1) & 7)) << 4); }
;                         else { const int cp = c - 2048, d = cp & 127; hd = cp >> 7; off = 16384 + (d >> 5) * 4096 + kv * 64 + (((d >> 3) & 3) << 4); }
;                         *(u32x4*)(KV + ((size_t)((((seq << 3) + hd) << (sshift - 6)) + tile) << 15) + off) = w; }
;                     else *(u32x4*)(rowp + bj * HALF) = w; } }
.LBB0_130:
	v_pk_mul_f32 v[56:57], v[56:57], v[68:69] op_sel_hi:[1,0]
	v_pk_mul_f32 v[54:55], v[54:55], v[68:69] op_sel_hi:[1,0]
	v_pk_mul_f32 v[58:59], v[52:53], v[68:69] op_sel_hi:[1,0]
	v_pk_mul_f32 v[52:53], v[50:51], v[68:69] op_sel_hi:[1,0]
	v_cvt_pk_bf16_f32 v50, v54, v55
	v_cvt_pk_bf16_f32 v51, v56, v57
	v_cvt_pk_bf16_f32 v52, v52, v53
	v_cvt_pk_bf16_f32 v53, v58, v59
	s_and_b64 vcc, exec, s[8:9]
	s_mov_b64 s[26:27], -1
	s_cbranch_vccnz .LBB0_132
	s_mov_b64 s[26:27], 0
	global_store_dwordx4 v[66:67], v[50:53], off offset:256

; __device__ __forceinline__ unsigned cvt_pk_bf16(float lo, float hi) { f32x2 v = {lo, hi}; bf16x2_t b = __builtin_convertvector(v, bf16x2_t); return __builtin_bit_cast(unsigned, b); }
;     __device__ __forceinline__ void operator()(const f32x4 (&acc)[2][2][4][2], const Unit& u, int wr, int wc, int fr, int fq) const {
;     ...
;                 for (int bj = 0; bj < 2; ++bj) { const f32x4 v0 = acc[ai][bj][m][0] * s, v1 = acc[ai][bj][m][1] * s; u32x4 w;
;                     w.x = cvt_pk_bf16(v0[0], v0[1]); w.y = cvt_pk_bf16(v0[2], v0[3]); w.z = cvt_pk_bf16(v1[0], v1[1]); w.w = cvt_pk_bf16(v1[2], v1[3]);
;                     if (kvt) { const int c = col0 + bj * HALF; int hd, off;
;                         if (colt < 2048) { const int cp = c - 1024, d = cp & 63; hd = (cp >> 6) & 7; off = (cp >> 9) * 8192 + kv * 128 + (((d >> 3) ^ ((kv >> 1) & 7)) << 4); }
;                         else { const int cp = c - 2048, d = cp & 127; hd = cp >> 7; off = 16384 + (d >> 5) * 4096 + kv * 64 + (((d >> 3) & 3) << 4); }
;                         *(u32x4*)(KV + ((size_t)((((seq << 3) + hd) << (sshift - 6)) + tile) << 15) + off) = w; }
;                     else *(u32x4*)(rowp + bj * HALF) = w; } }
.LBB0_138:
	v_pk_mul_f32 v[40:41], v[40:41], v[52:53] op_sel_hi:[1,0]
	v_pk_mul_f32 v[38:39], v[38:39], v[52:53] op_sel_hi:[1,0]
	v_pk_mul_f32 v[42:43], v[36:37], v[52:53] op_sel_hi:[1,0]
	v_pk_mul_f32 v[36:37], v[34:35], v[52:53] op_sel_hi:[1,0]
	v_cvt_pk_bf16_f32 v34, v38, v39
	v_cvt_pk_bf16_f32 v35, v40, v41
	v_cvt_pk_bf16_f32 v36, v36, v37
	v_cvt_pk_bf16_f32 v37, v42, v43
	s_and_b64 vcc, exec, s[8:9]
	s_mov_b64 s[26:27], -1
	s_cbranch_vccnz .LBB0_140
	s_mov_b64 s[26:27], 0
	global_store_dwordx4 v[50:51], v[34:37], off offset:256

; __device__ __forceinline__ unsigned cvt_pk_bf16(float lo, float hi) { f32x2 v = {lo, hi}; bf16x2_t b = __builtin_convertvector(v, bf16x2_t); return __builtin_bit_cast(unsigned, b); }
;     __device__ __forceinline__ void operator()(const f32x4 (&acc)[2][2][4][2], const Unit& u, int wr, int wc, int fr, int fq) const {
;     ...
;                 for (int bj = 0; bj < 2; ++bj) { const f32x4 v0 = acc[ai][bj][m][0] * s, v1 = acc[ai][bj][m][1] * s; u32x4 w;
;                     w.x = cvt_pk_bf16(v0[0], v0[1]); w.y = cvt_pk_bf16(v0[2], v0[3]); w.z = cvt_pk_bf16(v1[0], v1[1]); w.w = cvt_pk_bf16(v1[2], v1[3]);
;                     if (kvt) { const int c = col0 + bj * HALF; int hd, off;
;                         if (colt < 2048) { const int cp = c - 1024, d = cp & 63; hd = (cp >> 6) & 7; off = (cp >> 9) * 8192 + kv * 128 + (((d >> 3) ^ ((kv >> 1) & 7)) << 4); }
;                         else { const int cp = c - 2048, d = cp & 127; hd = cp >> 7; off = 16384 + (d >> 5) * 4096 + kv * 64 + (((d >> 3) & 3) << 4); }
;                         *(u32x4*)(KV + ((size_t)((((seq << 3) + hd) << (sshift - 6)) + tile) << 15) + off) = w; }
;                     else *(u32x4*)(rowp + bj * HALF) = w; } }
.LBB0_146:
	v_pk_mul_f32 v[24:25], v[24:25], v[36:37] op_sel_hi:[1,0]
	v_pk_mul_f32 v[22:23], v[22:23], v[36:37] op_sel_hi:[1,0]
	v_pk_mul_f32 v[26:27], v[20:21], v[36:37] op_sel_hi:[1,0]
	v_pk_mul_f32 v[20:21], v[18:19], v[36:37] op_sel_hi:[1,0]
	v_cvt_pk_bf16_f32 v18, v22, v23
	v_cvt_pk_bf16_f32 v19, v24, v25
	v_cvt_pk_bf16_f32 v20, v20, v21
	v_cvt_pk_bf16_f32 v21, v26, v27
	s_and_b64 vcc, exec, s[8:9]
	s_mov_b64 s[26:27], -1
	s_cbranch_vccnz .LBB0_148
	s_mov_b64 s[26:27], 0
	global_store_dwordx4 v[34:35], v[18:21], off offset:256

; __device__ __forceinline__ unsigned cvt_pk_bf16(float lo, float hi) { f32x2 v = {lo, hi}; bf16x2_t b = __builtin_convertvector(v, bf16x2_t); return __builtin_bit_cast(unsigned, b); }
;     __device__ __forceinline__ void operator()(const f32x4 (&acc)[2][2][4][2], const Unit& u, int wr, int wc, int fr, int fq) const {
;     ...
;                 for (int bj = 0; bj < 2; ++bj) { const f32x4 v0 = acc[ai][bj][m][0] * s, v1 = acc[ai][bj][m][1] * s; u32x4 w;
;                     w.x = cvt_pk_bf16(v0[0], v0[1]); w.y = cvt_pk_bf16(v0[2], v0[3]); w.z = cvt_pk_bf16(v1[0], v1[1]); w.w = cvt_pk_bf16(v1[2], v1[3]);
;                     if (kvt) { const int c = col0 + bj * HALF; int hd, off;
;                         if (colt < 2048) { const int cp = c - 1024, d = cp & 63; hd = (cp >> 6) & 7; off = (cp >> 9) * 8192 + kv * 128 + (((d >> 3) ^ ((kv >> 1) & 7)) << 4); }
;                         else { const int cp = c - 2048, d = cp & 127; hd = cp >> 7; off = 16384 + (d >> 5) * 4096 + kv * 64 + (((d >> 3) & 3) << 4); }
;                         *(u32x4*)(KV + ((size_t)((((seq << 3) + hd) << (sshift - 6)) + tile) << 15) + off) = w; }
;                     else *(u32x4*)(rowp + bj * HALF) = w; } }
.LBB0_154:
	v_pk_mul_f32 v[8:9], v[8:9], v[20:21] op_sel_hi:[1,0]
	v_pk_mul_f32 v[6:7], v[6:7], v[20:21] op_sel_hi:[1,0]
	v_pk_mul_f32 v[10:11], v[4:5], v[20:21] op_sel_hi:[1,0]
	v_pk_mul_f32 v[4:5], v[2:3], v[20:21] op_sel_hi:[1,0]
	v_cvt_pk_bf16_f32 v2, v6, v7
	v_cvt_pk_bf16_f32 v3, v8, v9
	v_cvt_pk_bf16_f32 v4, v4, v5
	v_cvt_pk_bf16_f32 v5, v10, v11
	s_and_b64 vcc, exec, s[8:9]
	s_mov_b64 s[8:9], -1
	s_cbranch_vccz .LBB0_157
	s_andn2_b64 vcc, exec, s[8:9]
	s_cbranch_vccz .LBB0_158
